# retention scan: the next v slice is requested two chunks ahead (second register set, chunk body unrolled x2) so the end-of-chunk wait no longer sits on HBM latency
# speedup vs baseline: 1.1504x; 1.0056x over previous
.LBB0_1313:
	s_or_b64 exec, exec, s[0:1]
	s_add_u32 s6, s94, 0x2a402800
	s_addc_u32 s7, s95, 0
	s_cmpk_gt_u32 s2, 0x7f
	s_waitcnt lgkmcnt(0)
	s_barrier
	s_cbranch_scc1 .LBB0_1326
	s_and_b32 s76, s2, 7
	s_lshr_b32 s77, s2, 3
	s_lshr_b32 s78, s77, 3
	s_lshl_b32 s72, s76, 1
	s_add_u32 s72, s72, s78
	s_and_b32 s73, s77, 7
	s_lshr_b32 s74, s72, 2
	s_and_b32 s75, s72, 3
	s_mov_b32 s82, 0xbd020aec
	s_cmp_eq_u32 s75, 1
	s_cselect_b32 s82, 0xbc8102b3, s82
	s_cmp_eq_u32 s75, 2
	s_cselect_b32 s82, 0xbc0080ac, s82
	s_cmp_eq_u32 s75, 3
	s_cselect_b32 s82, 0xbb80402b, s82
	v_lshrrev_b32_e32 v210, 6, v198
	v_and_b32_e32 v211, 15, v198
	v_bfe_u32 v212, v198, 4, 2
	v_readfirstlane_b32 s71, v210
	v_lshl_or_b32 v213, v210, 4, v211
	v_add_u32_e32 v213, 1, v213
	v_cvt_f32_i32_e32 v213, v213
	v_mul_f32_e32 v213, s82, v213
	v_mul_f32_e32 v213, 0x3fb8aa3b, v213
	v_exp_f32_e32 v202, v213
	v_mov_b32_e32 v213, 0x43000000
	v_mul_f32_e32 v213, s82, v213
	v_mul_f32_e32 v213, 0x3fb8aa3b, v213
	v_exp_f32_e32 v204, v213
	s_nop 1
	v_mov_b32_e32 v203, v202
	v_mov_b32_e32 v205, v204
	v_lshlrev_b32_e32 v192, 4, v211
	v_lshl_add_u32 v192, v212, 8, v192
	v_lshlrev_b32_e32 v193, 11, v211
	v_lshl_add_u32 v193, v212, 4, v193
	v_and_b32_e32 v213, 63, v198
	v_lshrrev_b32_e32 v195, 3, v213
	v_and_b32_e32 v215, 7, v213
	v_mul_u32_u24_e32 v214, 144, v195
	v_lshl_add_u32 v215, v215, 4, v214
	v_and_b32_e32 v214, 7, v213
	v_lshlrev_b32_e32 v195, 12, v195
	v_lshl_add_u32 v195, v214, 4, v195
	v_add_u32_e32 v220, 0x8000, v195
	v_mul_u32_u24_e32 v214, 144, v211
	v_lshl_add_u32 v214, v212, 3, v214
	v_mul_u32_u24_e32 v213, 2304, v210
	v_add_u32_e32 v213, 102400, v213
	v_add_u32_e32 v214, v214, v213
	v_add_u32_e32 v215, v215, v213
	v_lshrrev_b32_e32 v213, 3, v198
	v_and_b32_e32 v194, 7, v198
	v_lshlrev_b32_e32 v194, 4, v194
	v_mul_u32_u24_e32 v201, 272, v213
	v_add_u32_e32 v201, v201, v194
	v_lshl_add_u32 v194, v213, 13, v194
	v_add_u32_e32 v201, 67584, v201
	v_mul_u32_u24_e32 v196, 528, v211
	v_lshl_add_u32 v200, v212, 3, v196
	v_lshl_add_u32 v200, v210, 6, v200
	v_add_u32_e32 v200, 33792, v200
	v_lshl_add_u32 v196, v212, 4, v196
	v_mul_u32_u24_e32 v197, 272, v211
	v_lshl_add_u32 v197, v212, 4, v197
	v_add_u32_e32 v197, 67584, v197
	v_lshlrev_b32_e32 v206, 13, v212
	v_lshl_add_u32 v206, v211, 2, v206
	v_add_u32_e32 v207, 2048, v206
	v_add_u32_e32 v208, 4096, v206
	v_add_u32_e32 v209, 6144, v206
	s_mov_b32 s76, 0x27402800
	s_lshl_b32 s77, s72, 20
	s_add_u32 s76, s76, s77
	s_lshl_b32 s77, s71, 12
	s_add_u32 s76, s76, s77
	s_add_u32 s62, s94, s76
	s_addc_u32 s63, s95, 0
	s_mov_b32 s76, 0x28403800
	s_lshl_b32 s77, s72, 21
	s_add_u32 s76, s76, s77
	s_lshl_b32 s77, s71, 13
	s_add_u32 s76, s76, s77
	s_add_u32 s64, s94, s76
	s_addc_u32 s65, s95, 0
	s_mov_b32 s76, 0x1a802800
	s_lshl_b32 s77, s74, 23
	s_add_u32 s76, s76, s77
	s_lshl_b32 s77, s71, 15
	s_add_u32 s76, s76, s77
	s_lshl_b32 s77, s75, 9
	s_add_u32 s76, s76, s77
	s_add_u32 s60, s94, s76
	s_addc_u32 s61, s95, 0
	s_mov_b32 s76, 0x23002800
	s_lshl_b32 s77, s72, 22
	s_add_u32 s76, s76, s77
	s_lshl_b32 s77, s73, 19
	s_add_u32 s76, s76, s77
	s_add_u32 s66, s94, s76
	s_addc_u32 s67, s95, 0
	s_mov_b32 s76, 0x2a402800
	s_lshl_b32 s77, s74, 24
	s_add_u32 s76, s76, s77
	s_lshl_b32 s77, s71, 16
	s_add_u32 s76, s76, s77
	s_lshl_b32 s77, s75, 10
	s_add_u32 s76, s76, s77
	s_lshl_b32 s77, s73, 7
	s_add_u32 s76, s76, s77
	s_add_u32 s68, s94, s76
	s_addc_u32 s69, s95, 0
	s_mov_b32 s76, 0x6500000
	s_lshl_b32 s77, s72, 19
	s_add_u32 s76, s76, s77
	s_lshl_b32 s77, s71, 16
	s_add_u32 s76, s76, s77
	s_lshl_b32 s77, s73, 8
	s_add_u32 s76, s76, s77
	s_add_u32 s44, s92, s76
	s_addc_u32 s45, s93, 0
	s_add_u32 s46, s44, 0x8000
	s_addc_u32 s47, s45, 0
	global_load_dwordx4 v[176:179], v194, s[66:67]
	global_load_dwordx4 v[180:183], v194, s[66:67] offset:128
	global_load_dwordx4 v[0:3], v193, s[60:61]
	global_load_dwordx4 v[4:7], v193, s[60:61] offset:64
	global_load_dwordx4 v[8:11], v193, s[60:61] offset:128
	global_load_dwordx4 v[12:15], v193, s[60:61] offset:192
	global_load_dwordx4 v[16:19], v193, s[60:61] offset:256
	global_load_dwordx4 v[20:23], v193, s[60:61] offset:320
	global_load_dwordx4 v[24:27], v193, s[60:61] offset:384
	global_load_dwordx4 v[28:31], v193, s[60:61] offset:448
	global_load_dwordx4 v[32:35], v192, s[62:63]
	global_load_dwordx4 v[36:39], v192, s[62:63] offset:1024
	global_load_dwordx4 v[40:43], v192, s[62:63] offset:2048
	global_load_dwordx4 v[44:47], v192, s[62:63] offset:3072
	global_load_dwordx4 v[48:51], v192, s[64:65] offset:-4096
	global_load_dwordx4 v[64:67], v192, s[64:65]
	global_load_dwordx4 v[52:55], v192, s[64:65] offset:-3072
	global_load_dwordx4 v[68:71], v192, s[64:65] offset:1024
	global_load_dwordx4 v[56:59], v192, s[64:65] offset:-2048
	global_load_dwordx4 v[72:75], v192, s[64:65] offset:2048
	global_load_dwordx4 v[60:63], v192, s[64:65] offset:-1024
	global_load_dwordx4 v[76:79], v192, s[64:65] offset:3072
	v_mov_b32_e32 v216, 0
	v_mov_b32_e32 v217, 0
	v_mov_b32_e32 v218, 0
	v_mov_b32_e32 v219, 0
	v_mov_b32_e32 v80, 0
	v_mov_b32_e32 v81, 0
	v_mov_b32_e32 v82, 0
	v_mov_b32_e32 v83, 0
	v_mov_b32_e32 v84, 0
	v_mov_b32_e32 v85, 0
	v_mov_b32_e32 v86, 0
	v_mov_b32_e32 v87, 0
	v_mov_b32_e32 v88, 0
	v_mov_b32_e32 v89, 0
	v_mov_b32_e32 v90, 0
	v_mov_b32_e32 v91, 0
	v_mov_b32_e32 v92, 0
	v_mov_b32_e32 v93, 0
	v_mov_b32_e32 v94, 0
	v_mov_b32_e32 v95, 0
	v_mov_b32_e32 v96, 0
	v_mov_b32_e32 v97, 0
	v_mov_b32_e32 v98, 0
	v_mov_b32_e32 v99, 0
	v_mov_b32_e32 v100, 0
	v_mov_b32_e32 v101, 0
	v_mov_b32_e32 v102, 0
	v_mov_b32_e32 v103, 0
	v_mov_b32_e32 v104, 0
	v_mov_b32_e32 v105, 0
	v_mov_b32_e32 v106, 0
	v_mov_b32_e32 v107, 0
	v_mov_b32_e32 v108, 0
	v_mov_b32_e32 v109, 0
	v_mov_b32_e32 v110, 0
	v_mov_b32_e32 v111, 0
	v_lshlrev_b32_e32 v213, 4, v198
	ds_write_b128 v213, v[216:219] offset:0
	ds_write_b128 v213, v[216:219] offset:8192
	ds_write_b128 v213, v[216:219] offset:16384
	ds_write_b128 v213, v[216:219] offset:24576
	ds_write_b128 v213, v[216:219] offset:32768
	s_waitcnt vmcnt(20)
	ds_write_b128 v201, v[176:179]
	ds_write_b128 v201, v[180:183] offset:128
	v_add_u32_e32 v201, 17408, v201
	s_add_u32 s60, s60, 0x40000
	s_addc_u32 s61, s61, 0
	s_add_u32 s62, s62, 0x8000
	s_addc_u32 s63, s63, 0
	s_add_u32 s64, s64, 0x10000
	s_addc_u32 s65, s65, 0
	s_add_u32 s66, s66, 0x100
	s_addc_u32 s67, s67, 0
	global_load_dwordx4 v[222:225], v194, s[66:67]
	global_load_dwordx4 v[226:229], v194, s[66:67] offset:128
	s_add_u32 s66, s66, 0x100
	s_addc_u32 s67, s67, 0
	s_mov_b32 s70, 0
	s_mov_b32 s80, 33792
	s_mov_b32 s81, 17408
	s_waitcnt vmcnt(0) lgkmcnt(0)
	s_barrier
.Lscan_chunk:
	global_load_dwordx4 v[176:179], v194, s[66:67]
	global_load_dwordx4 v[180:183], v194, s[66:67] offset:128
	ds_read_b128 v[144:147], v196 offset:0
	ds_read_b128 v[148:151], v196 offset:8448
	ds_read_b128 v[152:155], v196 offset:16896
	ds_read_b128 v[156:159], v196 offset:25344
	ds_read_b128 v[160:163], v196 offset:64
	ds_read_b128 v[164:167], v196 offset:8512
	ds_read_b128 v[168:171], v196 offset:16960
	s_waitcnt lgkmcnt(6)
	s_waitcnt vmcnt(23)
	v_mfma_f32_16x16x32_bf16 v[112:115], v[144:147], v[0:3], 0
	ds_read_b128 v[172:175], v196 offset:25408
	s_waitcnt lgkmcnt(6)
	v_mfma_f32_16x16x32_bf16 v[116:119], v[148:151], v[0:3], 0
	ds_read_b128 v[144:147], v196 offset:128
	s_waitcnt lgkmcnt(6)
	v_mfma_f32_16x16x32_bf16 v[120:123], v[152:155], v[0:3], 0
	ds_read_b128 v[148:151], v196 offset:8576
	s_waitcnt lgkmcnt(6)
	v_mfma_f32_16x16x32_bf16 v[124:127], v[156:159], v[0:3], 0
	global_load_dwordx4 v[0:3], v193, s[60:61]
	ds_read_b128 v[152:155], v196 offset:17024
	s_waitcnt lgkmcnt(6)
	s_waitcnt vmcnt(23)
	v_mfma_f32_16x16x32_bf16 v[112:115], v[160:163], v[4:7], v[112:115]
	ds_read_b128 v[156:159], v196 offset:25472
	s_waitcnt lgkmcnt(6)
	v_mfma_f32_16x16x32_bf16 v[116:119], v[164:167], v[4:7], v[116:119]
	ds_read_b128 v[160:163], v196 offset:192
	s_waitcnt lgkmcnt(6)
	v_mfma_f32_16x16x32_bf16 v[120:123], v[168:171], v[4:7], v[120:123]
	ds_read_b128 v[164:167], v196 offset:8640
	s_waitcnt lgkmcnt(6)
	v_mfma_f32_16x16x32_bf16 v[124:127], v[172:175], v[4:7], v[124:127]
	global_load_dwordx4 v[4:7], v193, s[60:61] offset:64
	ds_read_b128 v[168:171], v196 offset:17088
	s_waitcnt lgkmcnt(6)
	s_waitcnt vmcnt(23)
	v_mfma_f32_16x16x32_bf16 v[112:115], v[144:147], v[8:11], v[112:115]
	ds_read_b128 v[172:175], v196 offset:25536
	s_waitcnt lgkmcnt(6)
	v_mfma_f32_16x16x32_bf16 v[116:119], v[148:151], v[8:11], v[116:119]
	ds_read_b128 v[144:147], v196 offset:256
	s_waitcnt lgkmcnt(6)
	v_mfma_f32_16x16x32_bf16 v[120:123], v[152:155], v[8:11], v[120:123]
	ds_read_b128 v[148:151], v196 offset:8704
	s_waitcnt lgkmcnt(6)
	v_mfma_f32_16x16x32_bf16 v[124:127], v[156:159], v[8:11], v[124:127]
	global_load_dwordx4 v[8:11], v193, s[60:61] offset:128
	ds_read_b128 v[152:155], v196 offset:17152
	s_waitcnt lgkmcnt(6)
	s_waitcnt vmcnt(23)
	v_mfma_f32_16x16x32_bf16 v[112:115], v[160:163], v[12:15], v[112:115]
	ds_read_b128 v[156:159], v196 offset:25600
	s_waitcnt lgkmcnt(6)
	v_mfma_f32_16x16x32_bf16 v[116:119], v[164:167], v[12:15], v[116:119]
	ds_read_b128 v[160:163], v196 offset:320
	s_waitcnt lgkmcnt(6)
	v_mfma_f32_16x16x32_bf16 v[120:123], v[168:171], v[12:15], v[120:123]
	ds_read_b128 v[164:167], v196 offset:8768
	s_waitcnt lgkmcnt(6)
	v_mfma_f32_16x16x32_bf16 v[124:127], v[172:175], v[12:15], v[124:127]
	global_load_dwordx4 v[12:15], v193, s[60:61] offset:192
	ds_read_b128 v[168:171], v196 offset:17216
	s_waitcnt lgkmcnt(6)
	s_waitcnt vmcnt(23)
	v_mfma_f32_16x16x32_bf16 v[112:115], v[144:147], v[16:19], v[112:115]
	ds_read_b128 v[172:175], v196 offset:25664
	s_waitcnt lgkmcnt(6)
	v_mfma_f32_16x16x32_bf16 v[116:119], v[148:151], v[16:19], v[116:119]
	ds_read_b128 v[144:147], v196 offset:384
	s_waitcnt lgkmcnt(6)
	v_mfma_f32_16x16x32_bf16 v[120:123], v[152:155], v[16:19], v[120:123]
	ds_read_b128 v[148:151], v196 offset:8832
	s_waitcnt lgkmcnt(6)
	v_mfma_f32_16x16x32_bf16 v[124:127], v[156:159], v[16:19], v[124:127]
	global_load_dwordx4 v[16:19], v193, s[60:61] offset:256
	ds_read_b128 v[152:155], v196 offset:17280
	s_waitcnt lgkmcnt(6)
	s_waitcnt vmcnt(23)
	v_mfma_f32_16x16x32_bf16 v[112:115], v[160:163], v[20:23], v[112:115]
	ds_read_b128 v[156:159], v196 offset:25728
	s_waitcnt lgkmcnt(6)
	v_mfma_f32_16x16x32_bf16 v[116:119], v[164:167], v[20:23], v[116:119]
	ds_read_b128 v[160:163], v196 offset:448
	s_waitcnt lgkmcnt(6)
	v_mfma_f32_16x16x32_bf16 v[120:123], v[168:171], v[20:23], v[120:123]
	ds_read_b128 v[164:167], v196 offset:8896
	s_waitcnt lgkmcnt(6)
	v_mfma_f32_16x16x32_bf16 v[124:127], v[172:175], v[20:23], v[124:127]
	global_load_dwordx4 v[20:23], v193, s[60:61] offset:320
	ds_read_b128 v[168:171], v196 offset:17344
	s_waitcnt lgkmcnt(6)
	s_waitcnt vmcnt(23)
	v_mfma_f32_16x16x32_bf16 v[112:115], v[144:147], v[24:27], v[112:115]
	ds_read_b128 v[172:175], v196 offset:25792
	s_waitcnt lgkmcnt(6)
	v_mfma_f32_16x16x32_bf16 v[116:119], v[148:151], v[24:27], v[116:119]
	ds_read_b128 v[144:147], v197 offset:0
	s_waitcnt lgkmcnt(6)
	v_mfma_f32_16x16x32_bf16 v[120:123], v[152:155], v[24:27], v[120:123]
	ds_read_b128 v[148:151], v197 offset:4352
	s_waitcnt lgkmcnt(6)
	v_mfma_f32_16x16x32_bf16 v[124:127], v[156:159], v[24:27], v[124:127]
	global_load_dwordx4 v[24:27], v193, s[60:61] offset:384
	ds_read_b128 v[152:155], v197 offset:8704
	s_waitcnt lgkmcnt(6)
	s_waitcnt vmcnt(23)
	v_mfma_f32_16x16x32_bf16 v[112:115], v[160:163], v[28:31], v[112:115]
	ds_read_b128 v[156:159], v197 offset:13056
	s_waitcnt lgkmcnt(6)
	v_mfma_f32_16x16x32_bf16 v[116:119], v[164:167], v[28:31], v[116:119]
	ds_read_b128 v[160:163], v197 offset:64
	s_waitcnt lgkmcnt(6)
	v_mfma_f32_16x16x32_bf16 v[120:123], v[168:171], v[28:31], v[120:123]
	ds_read_b128 v[164:167], v197 offset:4416
	s_waitcnt lgkmcnt(6)
	v_mfma_f32_16x16x32_bf16 v[124:127], v[172:175], v[28:31], v[124:127]
	global_load_dwordx4 v[28:31], v193, s[60:61] offset:448
	ds_read_b128 v[168:171], v197 offset:8768
	s_waitcnt lgkmcnt(6)
	s_waitcnt vmcnt(23)
	v_mfma_f32_16x16x32_bf16 v[128:131], v[144:147], v[32:35], 0
	ds_read_b128 v[172:175], v197 offset:13120
	s_waitcnt lgkmcnt(6)
	v_mfma_f32_16x16x32_bf16 v[132:135], v[148:151], v[32:35], 0
	ds_read_b128 v[144:147], v197 offset:128
	s_waitcnt lgkmcnt(6)
	v_mfma_f32_16x16x32_bf16 v[136:139], v[152:155], v[32:35], 0
	ds_read_b128 v[148:151], v197 offset:4480
	s_waitcnt lgkmcnt(6)
	v_mfma_f32_16x16x32_bf16 v[140:143], v[156:159], v[32:35], 0
	global_load_dwordx4 v[32:35], v192, s[62:63]
	ds_read_b128 v[152:155], v197 offset:8832
	s_waitcnt lgkmcnt(6)
	s_waitcnt vmcnt(23)
	v_mfma_f32_16x16x32_bf16 v[128:131], v[160:163], v[36:39], v[128:131]
	ds_read_b128 v[156:159], v197 offset:13184
	s_waitcnt lgkmcnt(6)
	v_mfma_f32_16x16x32_bf16 v[132:135], v[164:167], v[36:39], v[132:135]
	ds_read_b128 v[160:163], v197 offset:192
	s_waitcnt lgkmcnt(6)
	v_mfma_f32_16x16x32_bf16 v[136:139], v[168:171], v[36:39], v[136:139]
	ds_read_b128 v[164:167], v197 offset:4544
	s_waitcnt lgkmcnt(6)
	v_mfma_f32_16x16x32_bf16 v[140:143], v[172:175], v[36:39], v[140:143]
	global_load_dwordx4 v[36:39], v192, s[62:63] offset:1024
	ds_read_b128 v[168:171], v197 offset:8896
	s_waitcnt lgkmcnt(6)
	s_waitcnt vmcnt(23)
	v_mfma_f32_16x16x32_bf16 v[128:131], v[144:147], v[40:43], v[128:131]
	ds_read_b128 v[172:175], v197 offset:13248
	s_waitcnt lgkmcnt(6)
	v_mfma_f32_16x16x32_bf16 v[132:135], v[148:151], v[40:43], v[132:135]
	s_waitcnt lgkmcnt(5)
	v_mfma_f32_16x16x32_bf16 v[136:139], v[152:155], v[40:43], v[136:139]
	s_waitcnt lgkmcnt(4)
	v_mfma_f32_16x16x32_bf16 v[140:143], v[156:159], v[40:43], v[140:143]
	global_load_dwordx4 v[40:43], v192, s[62:63] offset:2048
	s_waitcnt lgkmcnt(3)
	s_waitcnt vmcnt(23)
	v_mfma_f32_16x16x32_bf16 v[128:131], v[160:163], v[44:47], v[128:131]
	s_waitcnt lgkmcnt(2)
	v_mfma_f32_16x16x32_bf16 v[132:135], v[164:167], v[44:47], v[132:135]
	s_waitcnt lgkmcnt(1)
	v_mfma_f32_16x16x32_bf16 v[136:139], v[168:171], v[44:47], v[136:139]
	s_waitcnt lgkmcnt(0)
	v_mfma_f32_16x16x32_bf16 v[140:143], v[172:175], v[44:47], v[140:143]
	global_load_dwordx4 v[44:47], v192, s[62:63] offset:3072
	s_nop 7
	v_pk_fma_f32 v[112:113], v[112:113], v[202:203], v[128:129]
	v_pk_fma_f32 v[114:115], v[114:115], v[202:203], v[130:131]
	v_pk_fma_f32 v[116:117], v[116:117], v[202:203], v[132:133]
	v_pk_fma_f32 v[118:119], v[118:119], v[202:203], v[134:135]
	v_pk_fma_f32 v[120:121], v[120:121], v[202:203], v[136:137]
	v_pk_fma_f32 v[122:123], v[122:123], v[202:203], v[138:139]
	v_pk_fma_f32 v[124:125], v[124:125], v[202:203], v[140:141]
	v_pk_fma_f32 v[126:127], v[126:127], v[202:203], v[142:143]
	v_cvt_pk_bf16_f32 v184, v112, v113
	v_cvt_pk_bf16_f32 v185, v114, v115
	v_cvt_pk_bf16_f32 v186, v116, v117
	v_cvt_pk_bf16_f32 v187, v118, v119
	v_cvt_pk_bf16_f32 v188, v120, v121
	v_cvt_pk_bf16_f32 v189, v122, v123
	v_cvt_pk_bf16_f32 v190, v124, v125
	v_cvt_pk_bf16_f32 v191, v126, v127
	ds_write_b64 v214, v[184:185]
	ds_write_b64 v214, v[186:187] offset:32
	ds_write_b64 v214, v[188:189] offset:64
	ds_write_b64 v214, v[190:191] offset:96
	s_waitcnt lgkmcnt(0)
	ds_read_b128 v[144:147], v215
	ds_read_b128 v[148:151], v215 offset:1152
	s_waitcnt lgkmcnt(0)
	global_store_dwordx4 v195, v[144:147], s[68:69]
	global_store_dwordx4 v220, v[148:151], s[68:69]
	v_pk_mul_f32 v[80:81], v[80:81], v[204:205]
	v_pk_mul_f32 v[82:83], v[82:83], v[204:205]
	v_pk_mul_f32 v[84:85], v[84:85], v[204:205]
	v_pk_mul_f32 v[86:87], v[86:87], v[204:205]
	v_pk_mul_f32 v[88:89], v[88:89], v[204:205]
	v_pk_mul_f32 v[90:91], v[90:91], v[204:205]
	v_pk_mul_f32 v[92:93], v[92:93], v[204:205]
	v_pk_mul_f32 v[94:95], v[94:95], v[204:205]
	v_pk_mul_f32 v[96:97], v[96:97], v[204:205]
	v_pk_mul_f32 v[98:99], v[98:99], v[204:205]
	v_pk_mul_f32 v[100:101], v[100:101], v[204:205]
	v_pk_mul_f32 v[102:103], v[102:103], v[204:205]
	v_pk_mul_f32 v[104:105], v[104:105], v[204:205]
	v_pk_mul_f32 v[106:107], v[106:107], v[204:205]
	v_pk_mul_f32 v[108:109], v[108:109], v[204:205]
	v_pk_mul_f32 v[110:111], v[110:111], v[204:205]
	ds_read_b128 v[144:147], v197 offset:0
	ds_read_b128 v[148:151], v197 offset:4352
	ds_read_b128 v[152:155], v197 offset:8704
	ds_read_b128 v[156:159], v197 offset:13056
	ds_read_b128 v[160:163], v197 offset:64
	ds_read_b128 v[164:167], v197 offset:4416
	ds_read_b128 v[168:171], v197 offset:8768
	s_waitcnt lgkmcnt(6)
	s_waitcnt vmcnt(22)
	v_mfma_f32_16x16x32_bf16 v[80:83], v[48:51], v[144:147], v[80:83]
	v_mfma_f32_16x16x32_bf16 v[96:99], v[64:67], v[144:147], v[96:99]
	ds_read_b128 v[172:175], v197 offset:13120
	s_waitcnt lgkmcnt(6)
	v_mfma_f32_16x16x32_bf16 v[84:87], v[48:51], v[148:151], v[84:87]
	v_mfma_f32_16x16x32_bf16 v[100:103], v[64:67], v[148:151], v[100:103]
	ds_read_b128 v[144:147], v197 offset:128
	s_waitcnt lgkmcnt(6)
	v_mfma_f32_16x16x32_bf16 v[88:91], v[48:51], v[152:155], v[88:91]
	v_mfma_f32_16x16x32_bf16 v[104:107], v[64:67], v[152:155], v[104:107]
	ds_read_b128 v[148:151], v197 offset:4480
	s_waitcnt lgkmcnt(6)
	v_mfma_f32_16x16x32_bf16 v[92:95], v[48:51], v[156:159], v[92:95]
	v_mfma_f32_16x16x32_bf16 v[108:111], v[64:67], v[156:159], v[108:111]
	global_load_dwordx4 v[48:51], v192, s[64:65] offset:-4096
	global_load_dwordx4 v[64:67], v192, s[64:65]
	ds_read_b128 v[152:155], v197 offset:8832
	s_waitcnt lgkmcnt(6)
	s_waitcnt vmcnt(22)
	v_mfma_f32_16x16x32_bf16 v[80:83], v[52:55], v[160:163], v[80:83]
	v_mfma_f32_16x16x32_bf16 v[96:99], v[68:71], v[160:163], v[96:99]
	ds_read_b128 v[156:159], v197 offset:13184
	s_waitcnt lgkmcnt(6)
	v_mfma_f32_16x16x32_bf16 v[84:87], v[52:55], v[164:167], v[84:87]
	v_mfma_f32_16x16x32_bf16 v[100:103], v[68:71], v[164:167], v[100:103]
	ds_read_b128 v[160:163], v197 offset:192
	s_waitcnt lgkmcnt(6)
	v_mfma_f32_16x16x32_bf16 v[88:91], v[52:55], v[168:171], v[88:91]
	v_mfma_f32_16x16x32_bf16 v[104:107], v[68:71], v[168:171], v[104:107]
	ds_read_b128 v[164:167], v197 offset:4544
	s_waitcnt lgkmcnt(6)
	v_mfma_f32_16x16x32_bf16 v[92:95], v[52:55], v[172:175], v[92:95]
	v_mfma_f32_16x16x32_bf16 v[108:111], v[68:71], v[172:175], v[108:111]
	global_load_dwordx4 v[52:55], v192, s[64:65] offset:-3072
	global_load_dwordx4 v[68:71], v192, s[64:65] offset:1024
	ds_read_b128 v[168:171], v197 offset:8896
	s_waitcnt lgkmcnt(6)
	s_waitcnt vmcnt(22)
	v_mfma_f32_16x16x32_bf16 v[80:83], v[56:59], v[144:147], v[80:83]
	v_mfma_f32_16x16x32_bf16 v[96:99], v[72:75], v[144:147], v[96:99]
	ds_read_b128 v[172:175], v197 offset:13248
	s_waitcnt lgkmcnt(6)
	v_mfma_f32_16x16x32_bf16 v[84:87], v[56:59], v[148:151], v[84:87]
	v_mfma_f32_16x16x32_bf16 v[100:103], v[72:75], v[148:151], v[100:103]
	s_waitcnt lgkmcnt(5)
	v_mfma_f32_16x16x32_bf16 v[88:91], v[56:59], v[152:155], v[88:91]
	v_mfma_f32_16x16x32_bf16 v[104:107], v[72:75], v[152:155], v[104:107]
	s_waitcnt lgkmcnt(4)
	v_mfma_f32_16x16x32_bf16 v[92:95], v[56:59], v[156:159], v[92:95]
	v_mfma_f32_16x16x32_bf16 v[108:111], v[72:75], v[156:159], v[108:111]
	global_load_dwordx4 v[56:59], v192, s[64:65] offset:-2048
	global_load_dwordx4 v[72:75], v192, s[64:65] offset:2048
	s_waitcnt lgkmcnt(3)
	s_waitcnt vmcnt(22)
	v_mfma_f32_16x16x32_bf16 v[80:83], v[60:63], v[160:163], v[80:83]
	v_mfma_f32_16x16x32_bf16 v[96:99], v[76:79], v[160:163], v[96:99]
	s_waitcnt lgkmcnt(2)
	v_mfma_f32_16x16x32_bf16 v[84:87], v[60:63], v[164:167], v[84:87]
	v_mfma_f32_16x16x32_bf16 v[100:103], v[76:79], v[164:167], v[100:103]
	s_waitcnt lgkmcnt(1)
	v_mfma_f32_16x16x32_bf16 v[88:91], v[60:63], v[168:171], v[88:91]
	v_mfma_f32_16x16x32_bf16 v[104:107], v[76:79], v[168:171], v[104:107]
	s_waitcnt lgkmcnt(0)
	v_mfma_f32_16x16x32_bf16 v[92:95], v[60:63], v[172:175], v[92:95]
	v_mfma_f32_16x16x32_bf16 v[108:111], v[76:79], v[172:175], v[108:111]
	global_load_dwordx4 v[60:63], v192, s[64:65] offset:-1024
	global_load_dwordx4 v[76:79], v192, s[64:65] offset:3072
	s_nop 7
	v_cvt_pk_bf16_f32 v144, v80, v81
	v_cvt_pk_bf16_f32 v145, v82, v83
	ds_write_b64 v200, v[144:145] offset:0
	v_cvt_pk_bf16_f32 v148, v84, v85
	v_cvt_pk_bf16_f32 v149, v86, v87
	ds_write_b64 v200, v[148:149] offset:8448
	v_cvt_pk_bf16_f32 v152, v88, v89
	v_cvt_pk_bf16_f32 v153, v90, v91
	ds_write_b64 v200, v[152:153] offset:16896
	v_cvt_pk_bf16_f32 v156, v92, v93
	v_cvt_pk_bf16_f32 v157, v94, v95
	ds_write_b64 v200, v[156:157] offset:25344
	v_cvt_pk_bf16_f32 v160, v96, v97
	v_cvt_pk_bf16_f32 v161, v98, v99
	ds_write_b64 v200, v[160:161] offset:32
	v_cvt_pk_bf16_f32 v164, v100, v101
	v_cvt_pk_bf16_f32 v165, v102, v103
	ds_write_b64 v200, v[164:165] offset:8480
	v_cvt_pk_bf16_f32 v168, v104, v105
	v_cvt_pk_bf16_f32 v169, v106, v107
	ds_write_b64 v200, v[168:169] offset:16928
	v_cvt_pk_bf16_f32 v172, v108, v109
	v_cvt_pk_bf16_f32 v173, v110, v111
	ds_write_b64 v200, v[172:173] offset:25376
	s_waitcnt vmcnt(46)
	ds_write_b128 v201, v[222:225]
	ds_write_b128 v201, v[226:229] offset:128
	v_add_u32_e32 v196, s80, v196
	v_subrev_u32_e32 v200, s80, v200
	v_add_u32_e32 v197, s81, v197
	v_subrev_u32_e32 v201, s81, v201
	s_sub_u32 s80, 0, s80
	s_sub_u32 s81, 0, s81
	s_add_u32 s68, s68, 0x80000
	s_addc_u32 s69, s69, 0
	s_add_u32 s70, s70, 1
	s_cmp_lt_u32 s70, 31
	s_cselect_b32 s83, 1, 0
	s_lshl_b32 s76, s83, 18
	s_add_u32 s60, s60, s76
	s_addc_u32 s61, s61, 0
	s_lshl_b32 s76, s83, 15
	s_add_u32 s62, s62, s76
	s_addc_u32 s63, s63, 0
	s_lshl_b32 s76, s83, 16
	s_add_u32 s64, s64, s76
	s_addc_u32 s65, s65, 0
	s_cmp_lt_u32 s70, 30
	s_cselect_b32 s76, 256, 0
	s_add_u32 s66, s66, s76
	s_addc_u32 s67, s67, 0
	s_waitcnt lgkmcnt(0)
	s_barrier
	global_load_dwordx4 v[222:225], v194, s[66:67]
	global_load_dwordx4 v[226:229], v194, s[66:67] offset:128
	ds_read_b128 v[144:147], v196 offset:0
	ds_read_b128 v[148:151], v196 offset:8448
	ds_read_b128 v[152:155], v196 offset:16896
	ds_read_b128 v[156:159], v196 offset:25344
	ds_read_b128 v[160:163], v196 offset:64
	ds_read_b128 v[164:167], v196 offset:8512
	ds_read_b128 v[168:171], v196 offset:16960
	s_waitcnt lgkmcnt(6)
	s_waitcnt vmcnt(23)
	v_mfma_f32_16x16x32_bf16 v[112:115], v[144:147], v[0:3], 0
	ds_read_b128 v[172:175], v196 offset:25408
	s_waitcnt lgkmcnt(6)
	v_mfma_f32_16x16x32_bf16 v[116:119], v[148:151], v[0:3], 0
	ds_read_b128 v[144:147], v196 offset:128
	s_waitcnt lgkmcnt(6)
	v_mfma_f32_16x16x32_bf16 v[120:123], v[152:155], v[0:3], 0
	ds_read_b128 v[148:151], v196 offset:8576
	s_waitcnt lgkmcnt(6)
	v_mfma_f32_16x16x32_bf16 v[124:127], v[156:159], v[0:3], 0
	global_load_dwordx4 v[0:3], v193, s[60:61]
	ds_read_b128 v[152:155], v196 offset:17024
	s_waitcnt lgkmcnt(6)
	s_waitcnt vmcnt(23)
	v_mfma_f32_16x16x32_bf16 v[112:115], v[160:163], v[4:7], v[112:115]
	ds_read_b128 v[156:159], v196 offset:25472
	s_waitcnt lgkmcnt(6)
	v_mfma_f32_16x16x32_bf16 v[116:119], v[164:167], v[4:7], v[116:119]
	ds_read_b128 v[160:163], v196 offset:192
	s_waitcnt lgkmcnt(6)
	v_mfma_f32_16x16x32_bf16 v[120:123], v[168:171], v[4:7], v[120:123]
	ds_read_b128 v[164:167], v196 offset:8640
	s_waitcnt lgkmcnt(6)
	v_mfma_f32_16x16x32_bf16 v[124:127], v[172:175], v[4:7], v[124:127]
	global_load_dwordx4 v[4:7], v193, s[60:61] offset:64
	ds_read_b128 v[168:171], v196 offset:17088
	s_waitcnt lgkmcnt(6)
	s_waitcnt vmcnt(23)
	v_mfma_f32_16x16x32_bf16 v[112:115], v[144:147], v[8:11], v[112:115]
	ds_read_b128 v[172:175], v196 offset:25536
	s_waitcnt lgkmcnt(6)
	v_mfma_f32_16x16x32_bf16 v[116:119], v[148:151], v[8:11], v[116:119]
	ds_read_b128 v[144:147], v196 offset:256
	s_waitcnt lgkmcnt(6)
	v_mfma_f32_16x16x32_bf16 v[120:123], v[152:155], v[8:11], v[120:123]
	ds_read_b128 v[148:151], v196 offset:8704
	s_waitcnt lgkmcnt(6)
	v_mfma_f32_16x16x32_bf16 v[124:127], v[156:159], v[8:11], v[124:127]
	global_load_dwordx4 v[8:11], v193, s[60:61] offset:128
	ds_read_b128 v[152:155], v196 offset:17152
	s_waitcnt lgkmcnt(6)
	s_waitcnt vmcnt(23)
	v_mfma_f32_16x16x32_bf16 v[112:115], v[160:163], v[12:15], v[112:115]
	ds_read_b128 v[156:159], v196 offset:25600
	s_waitcnt lgkmcnt(6)
	v_mfma_f32_16x16x32_bf16 v[116:119], v[164:167], v[12:15], v[116:119]
	ds_read_b128 v[160:163], v196 offset:320
	s_waitcnt lgkmcnt(6)
	v_mfma_f32_16x16x32_bf16 v[120:123], v[168:171], v[12:15], v[120:123]
	ds_read_b128 v[164:167], v196 offset:8768
	s_waitcnt lgkmcnt(6)
	v_mfma_f32_16x16x32_bf16 v[124:127], v[172:175], v[12:15], v[124:127]
	global_load_dwordx4 v[12:15], v193, s[60:61] offset:192
	ds_read_b128 v[168:171], v196 offset:17216
	s_waitcnt lgkmcnt(6)
	s_waitcnt vmcnt(23)
	v_mfma_f32_16x16x32_bf16 v[112:115], v[144:147], v[16:19], v[112:115]
	ds_read_b128 v[172:175], v196 offset:25664
	s_waitcnt lgkmcnt(6)
	v_mfma_f32_16x16x32_bf16 v[116:119], v[148:151], v[16:19], v[116:119]
	ds_read_b128 v[144:147], v196 offset:384
	s_waitcnt lgkmcnt(6)
	v_mfma_f32_16x16x32_bf16 v[120:123], v[152:155], v[16:19], v[120:123]
	ds_read_b128 v[148:151], v196 offset:8832
	s_waitcnt lgkmcnt(6)
	v_mfma_f32_16x16x32_bf16 v[124:127], v[156:159], v[16:19], v[124:127]
	global_load_dwordx4 v[16:19], v193, s[60:61] offset:256
	ds_read_b128 v[152:155], v196 offset:17280
	s_waitcnt lgkmcnt(6)
	s_waitcnt vmcnt(23)
	v_mfma_f32_16x16x32_bf16 v[112:115], v[160:163], v[20:23], v[112:115]
	ds_read_b128 v[156:159], v196 offset:25728
	s_waitcnt lgkmcnt(6)
	v_mfma_f32_16x16x32_bf16 v[116:119], v[164:167], v[20:23], v[116:119]
	ds_read_b128 v[160:163], v196 offset:448
	s_waitcnt lgkmcnt(6)
	v_mfma_f32_16x16x32_bf16 v[120:123], v[168:171], v[20:23], v[120:123]
	ds_read_b128 v[164:167], v196 offset:8896
	s_waitcnt lgkmcnt(6)
	v_mfma_f32_16x16x32_bf16 v[124:127], v[172:175], v[20:23], v[124:127]
	global_load_dwordx4 v[20:23], v193, s[60:61] offset:320
	ds_read_b128 v[168:171], v196 offset:17344
	s_waitcnt lgkmcnt(6)
	s_waitcnt vmcnt(23)
	v_mfma_f32_16x16x32_bf16 v[112:115], v[144:147], v[24:27], v[112:115]
	ds_read_b128 v[172:175], v196 offset:25792
	s_waitcnt lgkmcnt(6)
	v_mfma_f32_16x16x32_bf16 v[116:119], v[148:151], v[24:27], v[116:119]
	ds_read_b128 v[144:147], v197 offset:0
	s_waitcnt lgkmcnt(6)
	v_mfma_f32_16x16x32_bf16 v[120:123], v[152:155], v[24:27], v[120:123]
	ds_read_b128 v[148:151], v197 offset:4352
	s_waitcnt lgkmcnt(6)
	v_mfma_f32_16x16x32_bf16 v[124:127], v[156:159], v[24:27], v[124:127]
	global_load_dwordx4 v[24:27], v193, s[60:61] offset:384
	ds_read_b128 v[152:155], v197 offset:8704
	s_waitcnt lgkmcnt(6)
	s_waitcnt vmcnt(23)
	v_mfma_f32_16x16x32_bf16 v[112:115], v[160:163], v[28:31], v[112:115]
	ds_read_b128 v[156:159], v197 offset:13056
	s_waitcnt lgkmcnt(6)
	v_mfma_f32_16x16x32_bf16 v[116:119], v[164:167], v[28:31], v[116:119]
	ds_read_b128 v[160:163], v197 offset:64
	s_waitcnt lgkmcnt(6)
	v_mfma_f32_16x16x32_bf16 v[120:123], v[168:171], v[28:31], v[120:123]
	ds_read_b128 v[164:167], v197 offset:4416
	s_waitcnt lgkmcnt(6)
	v_mfma_f32_16x16x32_bf16 v[124:127], v[172:175], v[28:31], v[124:127]
	global_load_dwordx4 v[28:31], v193, s[60:61] offset:448
	ds_read_b128 v[168:171], v197 offset:8768
	s_waitcnt lgkmcnt(6)
	s_waitcnt vmcnt(23)
	v_mfma_f32_16x16x32_bf16 v[128:131], v[144:147], v[32:35], 0
	ds_read_b128 v[172:175], v197 offset:13120
	s_waitcnt lgkmcnt(6)
	v_mfma_f32_16x16x32_bf16 v[132:135], v[148:151], v[32:35], 0
	ds_read_b128 v[144:147], v197 offset:128
	s_waitcnt lgkmcnt(6)
	v_mfma_f32_16x16x32_bf16 v[136:139], v[152:155], v[32:35], 0
	ds_read_b128 v[148:151], v197 offset:4480
	s_waitcnt lgkmcnt(6)
	v_mfma_f32_16x16x32_bf16 v[140:143], v[156:159], v[32:35], 0
	global_load_dwordx4 v[32:35], v192, s[62:63]
	ds_read_b128 v[152:155], v197 offset:8832
	s_waitcnt lgkmcnt(6)
	s_waitcnt vmcnt(23)
	v_mfma_f32_16x16x32_bf16 v[128:131], v[160:163], v[36:39], v[128:131]
	ds_read_b128 v[156:159], v197 offset:13184
	s_waitcnt lgkmcnt(6)
	v_mfma_f32_16x16x32_bf16 v[132:135], v[164:167], v[36:39], v[132:135]
	ds_read_b128 v[160:163], v197 offset:192
	s_waitcnt lgkmcnt(6)
	v_mfma_f32_16x16x32_bf16 v[136:139], v[168:171], v[36:39], v[136:139]
	ds_read_b128 v[164:167], v197 offset:4544
	s_waitcnt lgkmcnt(6)
	v_mfma_f32_16x16x32_bf16 v[140:143], v[172:175], v[36:39], v[140:143]
	global_load_dwordx4 v[36:39], v192, s[62:63] offset:1024
	ds_read_b128 v[168:171], v197 offset:8896
	s_waitcnt lgkmcnt(6)
	s_waitcnt vmcnt(23)
	v_mfma_f32_16x16x32_bf16 v[128:131], v[144:147], v[40:43], v[128:131]
	ds_read_b128 v[172:175], v197 offset:13248
	s_waitcnt lgkmcnt(6)
	v_mfma_f32_16x16x32_bf16 v[132:135], v[148:151], v[40:43], v[132:135]
	s_waitcnt lgkmcnt(5)
	v_mfma_f32_16x16x32_bf16 v[136:139], v[152:155], v[40:43], v[136:139]
	s_waitcnt lgkmcnt(4)
	v_mfma_f32_16x16x32_bf16 v[140:143], v[156:159], v[40:43], v[140:143]
	global_load_dwordx4 v[40:43], v192, s[62:63] offset:2048
	s_waitcnt lgkmcnt(3)
	s_waitcnt vmcnt(23)
	v_mfma_f32_16x16x32_bf16 v[128:131], v[160:163], v[44:47], v[128:131]
	s_waitcnt lgkmcnt(2)
	v_mfma_f32_16x16x32_bf16 v[132:135], v[164:167], v[44:47], v[132:135]
	s_waitcnt lgkmcnt(1)
	v_mfma_f32_16x16x32_bf16 v[136:139], v[168:171], v[44:47], v[136:139]
	s_waitcnt lgkmcnt(0)
	v_mfma_f32_16x16x32_bf16 v[140:143], v[172:175], v[44:47], v[140:143]
	global_load_dwordx4 v[44:47], v192, s[62:63] offset:3072
	s_nop 7
	v_pk_fma_f32 v[112:113], v[112:113], v[202:203], v[128:129]
	v_pk_fma_f32 v[114:115], v[114:115], v[202:203], v[130:131]
	v_pk_fma_f32 v[116:117], v[116:117], v[202:203], v[132:133]
	v_pk_fma_f32 v[118:119], v[118:119], v[202:203], v[134:135]
	v_pk_fma_f32 v[120:121], v[120:121], v[202:203], v[136:137]
	v_pk_fma_f32 v[122:123], v[122:123], v[202:203], v[138:139]
	v_pk_fma_f32 v[124:125], v[124:125], v[202:203], v[140:141]
	v_pk_fma_f32 v[126:127], v[126:127], v[202:203], v[142:143]
	v_cvt_pk_bf16_f32 v184, v112, v113
	v_cvt_pk_bf16_f32 v185, v114, v115
	v_cvt_pk_bf16_f32 v186, v116, v117
	v_cvt_pk_bf16_f32 v187, v118, v119
	v_cvt_pk_bf16_f32 v188, v120, v121
	v_cvt_pk_bf16_f32 v189, v122, v123
	v_cvt_pk_bf16_f32 v190, v124, v125
	v_cvt_pk_bf16_f32 v191, v126, v127
	ds_write_b64 v214, v[184:185]
	ds_write_b64 v214, v[186:187] offset:32
	ds_write_b64 v214, v[188:189] offset:64
	ds_write_b64 v214, v[190:191] offset:96
	s_waitcnt lgkmcnt(0)
	ds_read_b128 v[144:147], v215
	ds_read_b128 v[148:151], v215 offset:1152
	s_waitcnt lgkmcnt(0)
	global_store_dwordx4 v195, v[144:147], s[68:69]
	global_store_dwordx4 v220, v[148:151], s[68:69]
	v_pk_mul_f32 v[80:81], v[80:81], v[204:205]
	v_pk_mul_f32 v[82:83], v[82:83], v[204:205]
	v_pk_mul_f32 v[84:85], v[84:85], v[204:205]
	v_pk_mul_f32 v[86:87], v[86:87], v[204:205]
	v_pk_mul_f32 v[88:89], v[88:89], v[204:205]
	v_pk_mul_f32 v[90:91], v[90:91], v[204:205]
	v_pk_mul_f32 v[92:93], v[92:93], v[204:205]
	v_pk_mul_f32 v[94:95], v[94:95], v[204:205]
	v_pk_mul_f32 v[96:97], v[96:97], v[204:205]
	v_pk_mul_f32 v[98:99], v[98:99], v[204:205]
	v_pk_mul_f32 v[100:101], v[100:101], v[204:205]
	v_pk_mul_f32 v[102:103], v[102:103], v[204:205]
	v_pk_mul_f32 v[104:105], v[104:105], v[204:205]
	v_pk_mul_f32 v[106:107], v[106:107], v[204:205]
	v_pk_mul_f32 v[108:109], v[108:109], v[204:205]
	v_pk_mul_f32 v[110:111], v[110:111], v[204:205]
	ds_read_b128 v[144:147], v197 offset:0
	ds_read_b128 v[148:151], v197 offset:4352
	ds_read_b128 v[152:155], v197 offset:8704
	ds_read_b128 v[156:159], v197 offset:13056
	ds_read_b128 v[160:163], v197 offset:64
	ds_read_b128 v[164:167], v197 offset:4416
	ds_read_b128 v[168:171], v197 offset:8768
	s_waitcnt lgkmcnt(6)
	s_waitcnt vmcnt(22)
	v_mfma_f32_16x16x32_bf16 v[80:83], v[48:51], v[144:147], v[80:83]
	v_mfma_f32_16x16x32_bf16 v[96:99], v[64:67], v[144:147], v[96:99]
	ds_read_b128 v[172:175], v197 offset:13120
	s_waitcnt lgkmcnt(6)
	v_mfma_f32_16x16x32_bf16 v[84:87], v[48:51], v[148:151], v[84:87]
	v_mfma_f32_16x16x32_bf16 v[100:103], v[64:67], v[148:151], v[100:103]
	ds_read_b128 v[144:147], v197 offset:128
	s_waitcnt lgkmcnt(6)
	v_mfma_f32_16x16x32_bf16 v[88:91], v[48:51], v[152:155], v[88:91]
	v_mfma_f32_16x16x32_bf16 v[104:107], v[64:67], v[152:155], v[104:107]
	ds_read_b128 v[148:151], v197 offset:4480
	s_waitcnt lgkmcnt(6)
	v_mfma_f32_16x16x32_bf16 v[92:95], v[48:51], v[156:159], v[92:95]
	v_mfma_f32_16x16x32_bf16 v[108:111], v[64:67], v[156:159], v[108:111]
	global_load_dwordx4 v[48:51], v192, s[64:65] offset:-4096
	global_load_dwordx4 v[64:67], v192, s[64:65]
	ds_read_b128 v[152:155], v197 offset:8832
	s_waitcnt lgkmcnt(6)
	s_waitcnt vmcnt(22)
	v_mfma_f32_16x16x32_bf16 v[80:83], v[52:55], v[160:163], v[80:83]
	v_mfma_f32_16x16x32_bf16 v[96:99], v[68:71], v[160:163], v[96:99]
	ds_read_b128 v[156:159], v197 offset:13184
	s_waitcnt lgkmcnt(6)
	v_mfma_f32_16x16x32_bf16 v[84:87], v[52:55], v[164:167], v[84:87]
	v_mfma_f32_16x16x32_bf16 v[100:103], v[68:71], v[164:167], v[100:103]
	ds_read_b128 v[160:163], v197 offset:192
	s_waitcnt lgkmcnt(6)
	v_mfma_f32_16x16x32_bf16 v[88:91], v[52:55], v[168:171], v[88:91]
	v_mfma_f32_16x16x32_bf16 v[104:107], v[68:71], v[168:171], v[104:107]
	ds_read_b128 v[164:167], v197 offset:4544
	s_waitcnt lgkmcnt(6)
	v_mfma_f32_16x16x32_bf16 v[92:95], v[52:55], v[172:175], v[92:95]
	v_mfma_f32_16x16x32_bf16 v[108:111], v[68:71], v[172:175], v[108:111]
	global_load_dwordx4 v[52:55], v192, s[64:65] offset:-3072
	global_load_dwordx4 v[68:71], v192, s[64:65] offset:1024
	ds_read_b128 v[168:171], v197 offset:8896
	s_waitcnt lgkmcnt(6)
	s_waitcnt vmcnt(22)
	v_mfma_f32_16x16x32_bf16 v[80:83], v[56:59], v[144:147], v[80:83]
	v_mfma_f32_16x16x32_bf16 v[96:99], v[72:75], v[144:147], v[96:99]
	ds_read_b128 v[172:175], v197 offset:13248
	s_waitcnt lgkmcnt(6)
	v_mfma_f32_16x16x32_bf16 v[84:87], v[56:59], v[148:151], v[84:87]
	v_mfma_f32_16x16x32_bf16 v[100:103], v[72:75], v[148:151], v[100:103]
	s_waitcnt lgkmcnt(5)
	v_mfma_f32_16x16x32_bf16 v[88:91], v[56:59], v[152:155], v[88:91]
	v_mfma_f32_16x16x32_bf16 v[104:107], v[72:75], v[152:155], v[104:107]
	s_waitcnt lgkmcnt(4)
	v_mfma_f32_16x16x32_bf16 v[92:95], v[56:59], v[156:159], v[92:95]
	v_mfma_f32_16x16x32_bf16 v[108:111], v[72:75], v[156:159], v[108:111]
	global_load_dwordx4 v[56:59], v192, s[64:65] offset:-2048
	global_load_dwordx4 v[72:75], v192, s[64:65] offset:2048
	s_waitcnt lgkmcnt(3)
	s_waitcnt vmcnt(22)
	v_mfma_f32_16x16x32_bf16 v[80:83], v[60:63], v[160:163], v[80:83]
	v_mfma_f32_16x16x32_bf16 v[96:99], v[76:79], v[160:163], v[96:99]
	s_waitcnt lgkmcnt(2)
	v_mfma_f32_16x16x32_bf16 v[84:87], v[60:63], v[164:167], v[84:87]
	v_mfma_f32_16x16x32_bf16 v[100:103], v[76:79], v[164:167], v[100:103]
	s_waitcnt lgkmcnt(1)
	v_mfma_f32_16x16x32_bf16 v[88:91], v[60:63], v[168:171], v[88:91]
	v_mfma_f32_16x16x32_bf16 v[104:107], v[76:79], v[168:171], v[104:107]
	s_waitcnt lgkmcnt(0)
	v_mfma_f32_16x16x32_bf16 v[92:95], v[60:63], v[172:175], v[92:95]
	v_mfma_f32_16x16x32_bf16 v[108:111], v[76:79], v[172:175], v[108:111]
	global_load_dwordx4 v[60:63], v192, s[64:65] offset:-1024
	global_load_dwordx4 v[76:79], v192, s[64:65] offset:3072
	s_nop 7
	v_cvt_pk_bf16_f32 v144, v80, v81
	v_cvt_pk_bf16_f32 v145, v82, v83
	ds_write_b64 v200, v[144:145] offset:0
	v_cvt_pk_bf16_f32 v148, v84, v85
	v_cvt_pk_bf16_f32 v149, v86, v87
	ds_write_b64 v200, v[148:149] offset:8448
	v_cvt_pk_bf16_f32 v152, v88, v89
	v_cvt_pk_bf16_f32 v153, v90, v91
	ds_write_b64 v200, v[152:153] offset:16896
	v_cvt_pk_bf16_f32 v156, v92, v93
	v_cvt_pk_bf16_f32 v157, v94, v95
	ds_write_b64 v200, v[156:157] offset:25344
	v_cvt_pk_bf16_f32 v160, v96, v97
	v_cvt_pk_bf16_f32 v161, v98, v99
	ds_write_b64 v200, v[160:161] offset:32
	v_cvt_pk_bf16_f32 v164, v100, v101
	v_cvt_pk_bf16_f32 v165, v102, v103
	ds_write_b64 v200, v[164:165] offset:8480
	v_cvt_pk_bf16_f32 v168, v104, v105
	v_cvt_pk_bf16_f32 v169, v106, v107
	ds_write_b64 v200, v[168:169] offset:16928
	v_cvt_pk_bf16_f32 v172, v108, v109
	v_cvt_pk_bf16_f32 v173, v110, v111
	ds_write_b64 v200, v[172:173] offset:25376
	s_waitcnt vmcnt(46)
	ds_write_b128 v201, v[176:179]
	ds_write_b128 v201, v[180:183] offset:128
	v_add_u32_e32 v196, s80, v196
	v_subrev_u32_e32 v200, s80, v200
	v_add_u32_e32 v197, s81, v197
	v_subrev_u32_e32 v201, s81, v201
	s_sub_u32 s80, 0, s80
	s_sub_u32 s81, 0, s81
	s_add_u32 s68, s68, 0x80000
	s_addc_u32 s69, s69, 0
	s_add_u32 s70, s70, 1
	s_cmp_lt_u32 s70, 31
	s_cselect_b32 s83, 1, 0
	s_lshl_b32 s76, s83, 18
	s_add_u32 s60, s60, s76
	s_addc_u32 s61, s61, 0
	s_lshl_b32 s76, s83, 15
	s_add_u32 s62, s62, s76
	s_addc_u32 s63, s63, 0
	s_lshl_b32 s76, s83, 16
	s_add_u32 s64, s64, s76
	s_addc_u32 s65, s65, 0
	s_cmp_lt_u32 s70, 30
	s_cselect_b32 s76, 256, 0
	s_add_u32 s66, s66, s76
	s_addc_u32 s67, s67, 0
	s_waitcnt lgkmcnt(0)
	s_barrier
	s_cmp_lt_u32 s70, 32
	s_cbranch_scc1 .Lscan_chunk
	s_waitcnt vmcnt(0)
	global_store_dword v206, v80, s[44:45]
	global_store_dword v207, v81, s[44:45]
	global_store_dword v208, v82, s[44:45]
	global_store_dword v209, v83, s[44:45]
	global_store_dword v206, v84, s[44:45] offset:64
	global_store_dword v207, v85, s[44:45] offset:64
	global_store_dword v208, v86, s[44:45] offset:64
	global_store_dword v209, v87, s[44:45] offset:64
	global_store_dword v206, v88, s[44:45] offset:128
	global_store_dword v207, v89, s[44:45] offset:128
	global_store_dword v208, v90, s[44:45] offset:128
	global_store_dword v209, v91, s[44:45] offset:128
	global_store_dword v206, v92, s[44:45] offset:192
	global_store_dword v207, v93, s[44:45] offset:192
	global_store_dword v208, v94, s[44:45] offset:192
	global_store_dword v209, v95, s[44:45] offset:192
	global_store_dword v206, v96, s[46:47]
	global_store_dword v207, v97, s[46:47]
	global_store_dword v208, v98, s[46:47]
	global_store_dword v209, v99, s[46:47]
	global_store_dword v206, v100, s[46:47] offset:64
	global_store_dword v207, v101, s[46:47] offset:64
	global_store_dword v208, v102, s[46:47] offset:64
	global_store_dword v209, v103, s[46:47] offset:64
	global_store_dword v206, v104, s[46:47] offset:128
	global_store_dword v207, v105, s[46:47] offset:128
	global_store_dword v208, v106, s[46:47] offset:128
	global_store_dword v209, v107, s[46:47] offset:128
	global_store_dword v206, v108, s[46:47] offset:192
	global_store_dword v207, v109, s[46:47] offset:192
	global_store_dword v208, v110, s[46:47] offset:192
	global_store_dword v209, v111, s[46:47] offset:192
